# speedup vs baseline: 1.0068x; 1.0038x over previous
; template <bool OUTBF>
; __device__ __forceinline__ void rmsnorm_phase(const float* __restrict__ in, const float* __restrict__ w, void* outp, int bid, int nb, int wv) {
;     ...
;   for (int row = bid * 8 + wid; row < T; row += nb * 8) {
;     const float4* pr = (const float4*)(in + (long)row * D);
;     float4 v[16];
;     float ss = 0.f;
; #pragma unroll
;     for (int i = 0; i < 16; ++i) {
;       v[i] = pr[lane + 64 * i];
;       ss += v[i].x * v[i].x + v[i].y * v[i].y + v[i].z * v[i].z + v[i].w * v[i].w;
;     }
;     ss = wavesum(ss, lane);
.LBB0_49:
	global_load_dwordx4 v[66:69], v[86:87], off offset:1024 nt
	global_load_dwordx4 v[70:73], v[86:87], off nt
	global_load_dwordx4 v[78:81], v[86:87], off offset:2048 nt
	global_load_dwordx4 v[74:77], v[86:87], off offset:3072 nt
	v_add_co_u32_e32 v88, vcc, s14, v86
	v_add_u32_e32 v82, s6, v82
	s_nop 0
	v_addc_co_u32_e32 v89, vcc, 0, v87, vcc
	v_add_co_u32_e32 v90, vcc, s13, v86
	s_waitcnt vmcnt(3)
	v_pk_mul_f32 v[144:145], v[68:69], v[68:69]
	v_addc_co_u32_e32 v91, vcc, 0, v87, vcc
	v_add_co_u32_e32 v92, vcc, s12, v86
	s_waitcnt vmcnt(2)
	v_pk_mul_f32 v[146:147], v[70:71], v[70:71]
	v_addc_co_u32_e32 v93, vcc, 0, v87, vcc
	global_load_dwordx4 v[100:103], v[88:89], off nt
	global_load_dwordx4 v[104:107], v[88:89], off offset:1024 nt
	global_load_dwordx4 v[108:111], v[88:89], off offset:2048 nt
	global_load_dwordx4 v[112:115], v[88:89], off offset:3072 nt
	global_load_dwordx4 v[116:119], v[90:91], off offset:1024 nt
	global_load_dwordx4 v[120:123], v[92:93], off offset:-4096 nt
	global_load_dwordx4 v[124:127], v[90:91], off offset:2048 nt
	s_nop 0
	global_load_dwordx4 v[88:91], v[90:91], off offset:3072 nt
	s_nop 0
	global_load_dwordx4 v[128:131], v[92:93], off nt
	global_load_dwordx4 v[132:135], v[92:93], off offset:1024 nt
	global_load_dwordx4 v[136:139], v[92:93], off offset:2048 nt
	global_load_dwordx4 v[140:143], v[92:93], off offset:3072 nt
	v_pk_mul_f32 v[92:93], v[66:67], v[66:67]
	v_pk_mul_f32 v[148:149], v[72:73], v[72:73]
	s_waitcnt vmcnt(13)
	v_pk_mul_f32 v[150:151], v[78:79], v[78:79]
	v_add_f32_e32 v198, v92, v93
	v_add_f32_e32 v199, v146, v147
	v_pk_mul_f32 v[152:153], v[80:81], v[80:81]
	s_waitcnt vmcnt(12)
	v_pk_mul_f32 v[154:155], v[74:75], v[74:75]
	v_add_f32_e32 v200, v150, v151
	v_add_f32_e32 v144, v198, v144
	v_add_f32_e32 v148, v199, v148
	v_pk_mul_f32 v[156:157], v[76:77], v[76:77]
	v_add_f32_e32 v201, v154, v155
	v_add_f32_e32 v152, v200, v152
	v_add_f32_e32 v148, v148, v149
	v_add_f32_e32 v156, v201, v156
	v_add_f32_e32 v149, v152, v153
	v_add_f32_e32 v152, v156, v157
	v_cmp_lt_i32_e32 vcc, s17, v82
	s_or_b64 s[10:11], vcc, s[10:11]
	v_lshl_add_u64 v[86:87], v[86:87], 0, s[4:5]
	s_waitcnt vmcnt(11)
	v_mov_b32_e32 v160, v101
	s_waitcnt vmcnt(10)
	v_mov_b32_e32 v161, v105
	v_mov_b32_e32 v158, v100
	v_mov_b32_e32 v159, v104
	s_waitcnt vmcnt(7)
	v_pk_mul_f32 v[150:151], v[116:117], v[116:117]
	v_pk_mul_f32 v[160:161], v[160:161], v[160:161]
	v_mov_b32_e32 v164, v109
	v_mov_b32_e32 v165, v113
	s_waitcnt vmcnt(6)
	v_pk_mul_f32 v[166:167], v[120:121], v[120:121]
	v_add_f32_e32 v198, v150, v151
	v_pk_fma_f32 v[150:151], v[158:159], v[158:159], v[160:161]
	v_add_f32_e32 v160, v144, v145
	v_mov_b32_e32 v162, v108
	v_mov_b32_e32 v163, v112
	v_pk_mul_f32 v[154:155], v[118:119], v[118:119]
	v_pk_mul_f32 v[168:169], v[122:123], v[122:123]
	v_pk_mul_f32 v[164:165], v[164:165], v[164:165]
	v_add_f32_e32 v166, v166, v167
	v_add_f32_e32 v148, v148, v160
	v_mov_b32_e32 v146, v110
	v_mov_b32_e32 v147, v114
	s_waitcnt vmcnt(5)
	v_pk_mul_f32 v[170:171], v[124:125], v[124:125]
	v_pk_fma_f32 v[158:159], v[162:163], v[162:163], v[164:165]
	v_add_f32_e32 v153, v198, v154
	v_add_f32_e32 v154, v166, v168
	v_add_f32_e32 v148, v148, v149
	v_pk_mul_f32 v[172:173], v[126:127], v[126:127]
	s_waitcnt vmcnt(4)
	v_pk_mul_f32 v[174:175], v[88:89], v[88:89]
	v_add_f32_e32 v167, v170, v171
	v_pk_fma_f32 v[144:145], v[146:147], v[146:147], v[158:159]
	v_add_f32_e32 v147, v154, v169
	v_add_f32_e32 v148, v148, v152
	v_mov_b32_e32 v92, v102
	v_mov_b32_e32 v93, v106
	v_pk_mul_f32 v[176:177], v[90:91], v[90:91]
	s_waitcnt vmcnt(3)
	v_pk_mul_f32 v[178:179], v[128:129], v[128:129]
	v_add_f32_e32 v170, v174, v175
	v_add_f32_e32 v156, v167, v172
	v_add_f32_e32 v146, v153, v155
	v_add_f32_e32 v147, v148, v147
	v_pk_mul_f32 v[180:181], v[130:131], v[130:131]
	s_waitcnt vmcnt(2)
	v_pk_mul_f32 v[182:183], v[132:133], v[132:133]
	v_add_f32_e32 v171, v178, v179
	v_add_f32_e32 v157, v170, v176
	v_pk_fma_f32 v[92:93], v[92:93], v[92:93], v[150:151]
	v_add_f32_e32 v150, v156, v173
	v_add_f32_e32 v146, v147, v146
	v_pk_mul_f32 v[184:185], v[134:135], v[134:135]
	s_waitcnt vmcnt(1)
	v_pk_mul_f32 v[186:187], v[136:137], v[136:137]
	v_add_f32_e32 v174, v182, v183
	v_add_f32_e32 v161, v171, v180
	v_add_f32_e32 v151, v157, v177
	v_add_f32_e32 v146, v146, v150
	v_pk_mul_f32 v[188:189], v[138:139], v[138:139]
	s_waitcnt vmcnt(0)
	v_pk_mul_f32 v[190:191], v[140:141], v[140:141]
	v_add_f32_e32 v175, v186, v187
	v_add_f32_e32 v162, v174, v184
	v_add_f32_e32 v153, v161, v181
	v_add_f32_e32 v146, v146, v151
	v_pk_mul_f32 v[192:193], v[142:143], v[142:143]
	v_add_f32_e32 v178, v190, v191
	v_add_f32_e32 v163, v175, v188
	v_add_f32_e32 v154, v162, v185
	v_add_f32_e32 v146, v146, v153
	v_add_f32_e32 v164, v178, v192
	v_add_f32_e32 v155, v163, v189
	v_add_f32_e32 v146, v146, v154
	v_mov_b32_e32 v194, v103
	v_mov_b32_e32 v195, v107
	v_add_f32_e32 v156, v164, v193
	v_add_f32_e32 v146, v146, v155
	v_pk_fma_f32 v[92:93], v[194:195], v[194:195], v[92:93]
	v_add_f32_e32 v146, v146, v156
	v_mov_b32_e32 v196, v111
	v_mov_b32_e32 v197, v115
	v_add_f32_e32 v92, v146, v92
	v_pk_fma_f32 v[144:145], v[196:197], v[196:197], v[144:145]
	v_add_f32_e32 v92, v92, v93
	v_add_f32_e32 v92, v92, v144
	v_add_f32_e32 v92, v92, v145
	ds_bpermute_b32 v93, v94, v92
	s_waitcnt lgkmcnt(0)
	v_add_f32_e32 v92, v92, v93
	ds_bpermute_b32 v93, v95, v92
	s_waitcnt lgkmcnt(0)
	v_add_f32_e32 v92, v92, v93
	ds_bpermute_b32 v93, v96, v92
	s_waitcnt lgkmcnt(0)
	v_add_f32_e32 v92, v92, v93
	ds_bpermute_b32 v93, v97, v92
	s_waitcnt lgkmcnt(0)
	v_add_f32_e32 v92, v92, v93
	ds_bpermute_b32 v93, v98, v92
	s_waitcnt lgkmcnt(0)
; template <bool OUTBF>
; __device__ __forceinline__ void rmsnorm_phase(const float* __restrict__ in, const float* __restrict__ w, void* outp, int bid, int nb, int wv) {
;     ...
;     ss = wavesum(ss, lane);
;     const float rs = rsqrtf(ss * (1.f / D) + 1e-6f);
; #pragma unroll
;     for (int i = 0; i < 16; ++i) {
;       float4 w4 = ((const float4*)w)[lane + 64 * i];
;       float4 y = make_float4(v[i].x * rs * w4.x, v[i].y * rs * w4.y, v[i].z * rs * w4.z, v[i].w * rs * w4.w);
;       if (OUTBF) {
;         u16x4 o; o[0] = f2bf(y.x); o[1] = f2bf(y.y); o[2] = f2bf(y.z); o[3] = f2bf(y.w);
	v_add_f32_e32 v92, v92, v93
	ds_bpermute_b32 v93, v99, v92
	s_waitcnt lgkmcnt(0)
	v_add_f32_e32 v92, v92, v93
	v_fmamk_f32 v92, v92, 0x39800000, v83
	v_mul_f32_e32 v93, 0x4b800000, v92
	v_cmp_gt_f32_e32 vcc, s7, v92
	s_nop 1
	v_cndmask_b32_e32 v92, v92, v93, vcc
	v_rsq_f32_e32 v92, v92
	s_nop 0
	v_mul_f32_e32 v93, 0x45800000, v92
	v_cndmask_b32_e32 v92, v92, v93, vcc
	v_pk_mul_f32 v[70:71], v[70:71], v[92:93] op_sel_hi:[1,0]
	v_pk_mul_f32 v[72:73], v[72:73], v[92:93] op_sel_hi:[1,0]
	v_pk_mul_f32 v[66:67], v[66:67], v[92:93] op_sel_hi:[1,0]
	v_pk_mul_f32 v[68:69], v[68:69], v[92:93] op_sel_hi:[1,0]
	v_pk_mul_f32 v[78:79], v[78:79], v[92:93] op_sel_hi:[1,0]
	v_pk_mul_f32 v[80:81], v[80:81], v[92:93] op_sel_hi:[1,0]
	v_pk_mul_f32 v[74:75], v[74:75], v[92:93] op_sel_hi:[1,0]
	v_pk_mul_f32 v[76:77], v[76:77], v[92:93] op_sel_hi:[1,0]
	v_pk_mul_f32 v[120:121], v[120:121], v[92:93] op_sel_hi:[1,0]
	v_pk_mul_f32 v[122:123], v[122:123], v[92:93] op_sel_hi:[1,0]
	v_pk_mul_f32 v[116:117], v[116:117], v[92:93] op_sel_hi:[1,0]
	v_pk_mul_f32 v[118:119], v[118:119], v[92:93] op_sel_hi:[1,0]
	v_pk_mul_f32 v[124:125], v[124:125], v[92:93] op_sel_hi:[1,0]
	v_pk_mul_f32 v[126:127], v[126:127], v[92:93] op_sel_hi:[1,0]
	v_pk_mul_f32 v[88:89], v[88:89], v[92:93] op_sel_hi:[1,0]
	v_pk_mul_f32 v[90:91], v[90:91], v[92:93] op_sel_hi:[1,0]
	v_pk_mul_f32 v[128:129], v[128:129], v[92:93] op_sel_hi:[1,0]
	v_pk_mul_f32 v[130:131], v[130:131], v[92:93] op_sel_hi:[1,0]
	v_pk_mul_f32 v[132:133], v[132:133], v[92:93] op_sel_hi:[1,0]
	v_pk_mul_f32 v[134:135], v[134:135], v[92:93] op_sel_hi:[1,0]
	v_pk_mul_f32 v[136:137], v[136:137], v[92:93] op_sel_hi:[1,0]
	v_pk_mul_f32 v[138:139], v[138:139], v[92:93] op_sel_hi:[1,0]
	v_pk_mul_f32 v[140:141], v[140:141], v[92:93] op_sel_hi:[1,0]
	v_pk_mul_f32 v[142:143], v[142:143], v[92:93] op_sel_hi:[1,0]
	v_pk_mul_f32 v[100:101], v[100:101], v[92:93] op_sel_hi:[1,0]
	v_pk_mul_f32 v[102:103], v[102:103], v[92:93] op_sel_hi:[1,0]
	v_pk_mul_f32 v[104:105], v[104:105], v[92:93] op_sel_hi:[1,0]
	v_pk_mul_f32 v[106:107], v[106:107], v[92:93] op_sel_hi:[1,0]
	v_pk_mul_f32 v[108:109], v[108:109], v[92:93] op_sel_hi:[1,0]
	v_pk_mul_f32 v[110:111], v[110:111], v[92:93] op_sel_hi:[1,0]
	v_pk_mul_f32 v[112:113], v[112:113], v[92:93] op_sel_hi:[1,0]
	v_pk_mul_f32 v[92:93], v[114:115], v[92:93] op_sel_hi:[1,0]
	v_pk_mul_f32 v[70:71], v[2:3], v[70:71]
	v_pk_mul_f32 v[72:73], v[4:5], v[72:73]
	v_pk_mul_f32 v[66:67], v[6:7], v[66:67]
	v_pk_mul_f32 v[68:69], v[8:9], v[68:69]
	v_pk_mul_f32 v[78:79], v[10:11], v[78:79]
	v_pk_mul_f32 v[80:81], v[12:13], v[80:81]
	v_pk_mul_f32 v[74:75], v[14:15], v[74:75]
	v_pk_mul_f32 v[76:77], v[16:17], v[76:77]
	v_pk_mul_f32 v[114:115], v[18:19], v[120:121]
	v_pk_mul_f32 v[120:121], v[20:21], v[122:123]
	v_pk_mul_f32 v[116:117], v[22:23], v[116:117]
	v_pk_mul_f32 v[118:119], v[24:25], v[118:119]
	v_pk_mul_f32 v[122:123], v[26:27], v[124:125]
	v_pk_mul_f32 v[124:125], v[28:29], v[126:127]
	v_pk_mul_f32 v[88:89], v[30:31], v[88:89]
	v_pk_mul_f32 v[90:91], v[32:33], v[90:91]
	v_pk_mul_f32 v[126:127], v[34:35], v[128:129]
	v_pk_mul_f32 v[128:129], v[36:37], v[130:131]
	v_pk_mul_f32 v[130:131], v[38:39], v[132:133]
	v_pk_mul_f32 v[132:133], v[40:41], v[134:135]
	v_pk_mul_f32 v[134:135], v[42:43], v[136:137]
	v_pk_mul_f32 v[136:137], v[44:45], v[138:139]
	v_pk_mul_f32 v[138:139], v[46:47], v[140:141]
	v_pk_mul_f32 v[140:141], v[48:49], v[142:143]
	v_pk_mul_f32 v[100:101], v[50:51], v[100:101]
	v_pk_mul_f32 v[102:103], v[52:53], v[102:103]
	v_pk_mul_f32 v[104:105], v[54:55], v[104:105]
	v_pk_mul_f32 v[106:107], v[56:57], v[106:107]
	v_pk_mul_f32 v[108:109], v[58:59], v[108:109]
	v_pk_mul_f32 v[110:111], v[60:61], v[110:111]
	v_pk_mul_f32 v[112:113], v[62:63], v[112:113]
	v_pk_mul_f32 v[92:93], v[64:65], v[92:93]
	v_bfe_u32 v142, v70, 16, 1
	v_bfe_u32 v143, v71, 16, 1
	v_bfe_u32 v144, v72, 16, 1
	v_bfe_u32 v145, v73, 16, 1
	v_bfe_u32 v146, v66, 16, 1
	v_bfe_u32 v147, v67, 16, 1
	v_bfe_u32 v148, v68, 16, 1
	v_bfe_u32 v149, v69, 16, 1
	v_bfe_u32 v150, v78, 16, 1
	v_bfe_u32 v151, v79, 16, 1
	v_bfe_u32 v152, v80, 16, 1
	v_bfe_u32 v153, v81, 16, 1
	v_bfe_u32 v154, v74, 16, 1
	v_bfe_u32 v155, v75, 16, 1
	v_bfe_u32 v156, v76, 16, 1
	v_bfe_u32 v157, v77, 16, 1
	v_bfe_u32 v158, v114, 16, 1
	v_bfe_u32 v159, v115, 16, 1
	v_bfe_u32 v160, v120, 16, 1
	v_bfe_u32 v161, v121, 16, 1
	v_bfe_u32 v162, v116, 16, 1
	v_bfe_u32 v163, v117, 16, 1
	v_bfe_u32 v164, v118, 16, 1
	v_bfe_u32 v165, v119, 16, 1
	v_bfe_u32 v166, v122, 16, 1
	v_bfe_u32 v167, v123, 16, 1
	v_bfe_u32 v168, v124, 16, 1
	v_bfe_u32 v169, v125, 16, 1
	v_bfe_u32 v170, v88, 16, 1
	v_bfe_u32 v171, v89, 16, 1
	v_bfe_u32 v172, v90, 16, 1
	v_bfe_u32 v173, v91, 16, 1
	v_bfe_u32 v174, v126, 16, 1
	v_bfe_u32 v175, v127, 16, 1
	v_bfe_u32 v176, v128, 16, 1
	v_bfe_u32 v177, v129, 16, 1
	v_bfe_u32 v178, v130, 16, 1
	v_bfe_u32 v179, v131, 16, 1
	v_bfe_u32 v180, v132, 16, 1
	v_bfe_u32 v181, v133, 16, 1
; template <bool OUTBF>
; __device__ __forceinline__ void rmsnorm_phase(const float* __restrict__ in, const float* __restrict__ w, void* outp, int bid, int nb, int wv) {
;     ...
;       float4 y = make_float4(v[i].x * rs * w4.x, v[i].y * rs * w4.y, v[i].z * rs * w4.z, v[i].w * rs * w4.w);
;       if (OUTBF) {
;         u16x4 o; o[0] = f2bf(y.x); o[1] = f2bf(y.y); o[2] = f2bf(y.z); o[3] = f2bf(y.w);
;         *(u16x4*)((bf16*)outp + (long)row * D + (lane + 64 * i) * 4) = o;
	v_bfe_u32 v182, v134, 16, 1
	v_bfe_u32 v183, v135, 16, 1
	v_bfe_u32 v184, v136, 16, 1
	v_bfe_u32 v185, v137, 16, 1
	v_bfe_u32 v186, v138, 16, 1
	v_bfe_u32 v187, v139, 16, 1
	v_bfe_u32 v188, v140, 16, 1
	v_bfe_u32 v189, v141, 16, 1
	v_bfe_u32 v190, v100, 16, 1
	v_bfe_u32 v191, v101, 16, 1
	v_bfe_u32 v192, v102, 16, 1
	v_bfe_u32 v193, v103, 16, 1
	v_bfe_u32 v194, v104, 16, 1
	v_bfe_u32 v195, v105, 16, 1
	v_bfe_u32 v196, v106, 16, 1
	v_bfe_u32 v197, v107, 16, 1
	v_bfe_u32 v198, v108, 16, 1
	v_bfe_u32 v199, v109, 16, 1
	v_bfe_u32 v200, v110, 16, 1
	v_bfe_u32 v201, v111, 16, 1
	v_bfe_u32 v202, v112, 16, 1
	v_bfe_u32 v203, v113, 16, 1
	v_bfe_u32 v204, v92, 16, 1
	v_bfe_u32 v205, v93, 16, 1
	v_add3_u32 v70, v70, v142, s15
	v_add3_u32 v71, v71, v143, s15
	v_add3_u32 v72, v72, v144, s15
	v_add3_u32 v73, v73, v145, s15
	v_add3_u32 v142, v66, v146, s15
	v_add3_u32 v143, v67, v147, s15
	v_add3_u32 v68, v68, v148, s15
	v_add3_u32 v69, v69, v149, s15
	v_add3_u32 v78, v78, v150, s15
	v_add3_u32 v79, v79, v151, s15
	v_add3_u32 v80, v80, v152, s15
	v_add3_u32 v81, v81, v153, s15
	v_add3_u32 v74, v74, v154, s15
	v_add3_u32 v75, v75, v155, s15
	v_add3_u32 v76, v76, v156, s15
	v_add3_u32 v77, v77, v157, s15
	v_add3_u32 v114, v114, v158, s15
	v_add3_u32 v115, v115, v159, s15
	v_add3_u32 v120, v120, v160, s15
	v_add3_u32 v121, v121, v161, s15
	v_add3_u32 v116, v116, v162, s15
	v_add3_u32 v117, v117, v163, s15
	v_add3_u32 v118, v118, v164, s15
	v_add3_u32 v119, v119, v165, s15
	v_add3_u32 v122, v122, v166, s15
	v_add3_u32 v123, v123, v167, s15
	v_add3_u32 v124, v124, v168, s15
	v_add3_u32 v125, v125, v169, s15
	v_add3_u32 v88, v88, v170, s15
	v_add3_u32 v89, v89, v171, s15
	v_add3_u32 v90, v90, v172, s15
	v_add3_u32 v91, v91, v173, s15
	v_add3_u32 v126, v126, v174, s15
	v_add3_u32 v127, v127, v175, s15
	v_add3_u32 v128, v128, v176, s15
	v_add3_u32 v129, v129, v177, s15
	v_add3_u32 v130, v130, v178, s15
	v_add3_u32 v131, v131, v179, s15
	v_add3_u32 v132, v132, v180, s15
	v_add3_u32 v133, v133, v181, s15
	v_add3_u32 v134, v134, v182, s15
	v_add3_u32 v135, v135, v183, s15
	v_add3_u32 v136, v136, v184, s15
	v_add3_u32 v137, v137, v185, s15
	v_add3_u32 v138, v138, v186, s15
	v_add3_u32 v139, v139, v187, s15
	v_add3_u32 v140, v140, v188, s15
	v_add3_u32 v141, v141, v189, s15
	v_add3_u32 v144, v100, v190, s15
	v_add3_u32 v145, v101, v191, s15
	v_add3_u32 v102, v102, v192, s15
	v_add3_u32 v103, v103, v193, s15
	v_add3_u32 v104, v104, v194, s15
	v_add3_u32 v146, v105, v195, s15
	v_add3_u32 v105, v106, v196, s15
	v_add3_u32 v106, v107, v197, s15
	v_add3_u32 v108, v108, v198, s15
	v_add3_u32 v109, v109, v199, s15
	v_add3_u32 v107, v110, v200, s15
	v_add3_u32 v110, v111, v201, s15
	v_add3_u32 v111, v112, v202, s15
	v_add3_u32 v112, v113, v203, s15
	v_add3_u32 v113, v92, v204, s15
	v_add3_u32 v147, v93, v205, s15
	v_perm_b32 v67, v73, v72, s16
	v_perm_b32 v66, v71, v70, s16
	v_perm_b32 v69, v69, v68, s16
	v_perm_b32 v68, v143, v142, s16
	v_perm_b32 v71, v81, v80, s16
	v_perm_b32 v70, v79, v78, s16
	v_perm_b32 v73, v77, v76, s16
	v_perm_b32 v72, v75, v74, s16
	v_perm_b32 v75, v121, v120, s16
	v_perm_b32 v74, v115, v114, s16
	v_perm_b32 v77, v119, v118, s16
	v_perm_b32 v76, v117, v116, s16
	v_perm_b32 v79, v125, v124, s16
	v_perm_b32 v78, v123, v122, s16
	v_perm_b32 v81, v91, v90, s16
	v_perm_b32 v80, v89, v88, s16
	v_perm_b32 v89, v129, v128, s16
	v_perm_b32 v88, v127, v126, s16
	v_perm_b32 v91, v133, v132, s16
	v_perm_b32 v90, v131, v130, s16
	v_perm_b32 v93, v137, v136, s16
	v_perm_b32 v92, v135, v134, s16
	v_perm_b32 v101, v141, v140, s16
	v_perm_b32 v100, v139, v138, s16
	v_perm_b32 v103, v103, v102, s16
	v_perm_b32 v102, v145, v144, s16
	v_perm_b32 v105, v106, v105, s16
	v_perm_b32 v104, v146, v104, s16
	v_perm_b32 v107, v110, v107, s16
	v_perm_b32 v106, v109, v108, s16
	v_perm_b32 v109, v147, v113, s16
	v_perm_b32 v108, v112, v111, s16
	global_store_dwordx2 v[84:85], v[66:67], off offset:-4096 nt
	global_store_dwordx2 v[84:85], v[68:69], off offset:-3584 nt
	global_store_dwordx2 v[84:85], v[70:71], off offset:-3072 nt
	global_store_dwordx2 v[84:85], v[72:73], off offset:-2560 nt
	global_store_dwordx2 v[84:85], v[74:75], off offset:-2048 nt
	global_store_dwordx2 v[84:85], v[76:77], off offset:-1536 nt
	global_store_dwordx2 v[84:85], v[78:79], off offset:-1024 nt
	global_store_dwordx2 v[84:85], v[80:81], off offset:-512 nt
	global_store_dwordx2 v[84:85], v[88:89], off nt
	global_store_dwordx2 v[84:85], v[90:91], off offset:512 nt
	global_store_dwordx2 v[84:85], v[92:93], off offset:1024 nt
	global_store_dwordx2 v[84:85], v[100:101], off offset:1536 nt
	global_store_dwordx2 v[84:85], v[102:103], off offset:2048 nt
	global_store_dwordx2 v[84:85], v[104:105], off offset:2560 nt
	global_store_dwordx2 v[84:85], v[106:107], off offset:3072 nt
	global_store_dwordx2 v[84:85], v[108:109], off offset:3584 nt
	v_lshl_add_u64 v[84:85], v[84:85], 0, s[8:9]
	s_andn2_b64 exec, exec, s[10:11]
	s_cbranch_execnz .LBB0_49
